# final phase: non-temporal hint on the f32 output stores (never re-read)
# speedup vs baseline: 1.0042x; 1.0042x over previous
.LBB0_693:
	v_lshl_add_u32 v166, s9, 8, v163
	v_ashrrev_i32_e32 v167, 31, v166
	v_lshlrev_b64 v[168:169], 10, v[166:167]
	v_lshl_add_u64 v[170:171], v[168:169], 0, v[164:165]
	v_lshl_add_u64 v[172:173], v[170:171], 1, s[28:29]
	v_mov_b32_e32 v198, v172
	v_mov_b32_e32 v199, v173
	v_mov_b32_e32 v182, v172
	v_mov_b32_e32 v183, v173
	s_mov_b64 s[42:43], 0x8000
	global_load_dwordx4 v[184:187], v[182:183], off
	global_load_dwordx4 v[212:215], v[182:183], off offset:256
	v_lshl_add_u64 v[182:183], v[182:183], 0, s[42:43]
	global_load_dwordx4 v[216:219], v[182:183], off
	global_load_dwordx4 v[220:223], v[182:183], off offset:256
	v_lshl_add_u64 v[182:183], v[182:183], 0, s[42:43]
	global_load_dwordx4 v[224:227], v[182:183], off
	global_load_dwordx4 v[228:231], v[182:183], off offset:256
	v_lshl_add_u64 v[182:183], v[182:183], 0, s[42:43]
	global_load_dwordx4 v[232:235], v[182:183], off
	global_load_dwordx4 v[236:239], v[182:183], off offset:256
	s_andn2_b64 vcc, exec, s[50:51]
	s_waitcnt vmcnt(7)
	v_mov_b32_e32 v178, v184
	v_mov_b32_e32 v179, v185
	v_mov_b32_e32 v180, v186
	v_mov_b32_e32 v181, v187
	v_lshlrev_b32_e32 v168, 16, v178
	v_and_b32_e32 v169, 0xffff0000, v178
	v_lshlrev_b32_e32 v178, 16, v179
	v_and_b32_e32 v179, 0xffff0000, v179
	v_pk_fma_f32 v[142:143], v[142:143], v[50:51], v[168:169]
	v_lshlrev_b32_e32 v168, 16, v180
	v_and_b32_e32 v169, 0xffff0000, v180
	v_pk_fma_f32 v[144:145], v[144:145], v[52:53], v[178:179]
	v_lshlrev_b32_e32 v178, 16, v181
	v_and_b32_e32 v179, 0xffff0000, v181
	v_pk_fma_f32 v[138:139], v[138:139], v[54:55], v[168:169]
	v_cndmask_b32_e64 v168, 0, 1, s[50:51]
	v_pk_fma_f32 v[140:141], v[140:141], v[56:57], v[178:179]
	v_cmp_ne_u32_e64 s[38:39], 1, v168
	v_lshl_add_u64 v[168:169], v[170:171], 2, s[16:17]
	s_cbranch_vccnz .LBB0_776
	global_store_dwordx4 v[168:169], v[142:145], off nt
	global_store_dwordx4 v[168:169], v[138:141], off offset:16 nt
	v_mov_b32_e32 v178, 0
	s_cbranch_execnz .LBB0_696

.LBB0_696:
	v_lshlrev_b64 v[138:139], 1, v[170:171]
	v_or_b32_e32 v138, 0x100, v138
	v_lshl_add_u64 v[138:139], s[28:29], 0, v[138:139]
	s_and_b64 vcc, exec, s[38:39]
	s_waitcnt vmcnt(7)
	v_mov_b32_e32 v140, v212
	v_mov_b32_e32 v141, v213
	v_mov_b32_e32 v142, v214
	v_mov_b32_e32 v143, v215
	v_lshlrev_b32_e32 v144, 16, v140
	v_and_b32_e32 v145, 0xffff0000, v140
	v_lshlrev_b32_e32 v140, 16, v141
	v_and_b32_e32 v141, 0xffff0000, v141
	v_pk_fma_f32 v[136:137], v[136:137], v[40:41], v[140:141]
	v_lshlrev_b32_e32 v140, 16, v142
	v_and_b32_e32 v141, 0xffff0000, v142
	v_lshlrev_b32_e32 v142, 16, v143
	v_and_b32_e32 v143, 0xffff0000, v143
	v_pk_fma_f32 v[134:135], v[134:135], v[38:39], v[144:145]
	v_pk_fma_f32 v[132:133], v[132:133], v[48:49], v[142:143]
	v_pk_fma_f32 v[130:131], v[130:131], v[46:47], v[140:141]
	s_cbranch_vccnz .LBB0_777
	global_store_dwordx4 v[168:169], v[134:137], off offset:512 nt
	global_store_dwordx4 v[168:169], v[130:133], off offset:528 nt
	s_cbranch_execnz .LBB0_699

.LBB0_703:
	v_or_b32_e32 v130, 16, v166
	s_waitcnt lgkmcnt(0)
	v_ashrrev_i32_e32 v131, 31, v130
	v_lshlrev_b64 v[132:133], 10, v[130:131]
	v_lshl_add_u64 v[134:135], v[132:133], 0, v[164:165]
	v_lshl_add_u64 v[136:137], v[134:135], 1, s[28:29]
	s_and_b64 vcc, exec, s[38:39]
	s_waitcnt vmcnt(7)
	v_mov_b32_e32 v138, v216
	v_mov_b32_e32 v139, v217
	v_mov_b32_e32 v140, v218
	v_mov_b32_e32 v141, v219
	v_lshlrev_b32_e32 v132, 16, v138
	v_and_b32_e32 v133, 0xffff0000, v138
	v_lshlrev_b32_e32 v138, 16, v139
	v_and_b32_e32 v139, 0xffff0000, v139
	v_pk_fma_f32 v[128:129], v[128:129], v[52:53], v[138:139]
	v_pk_fma_f32 v[126:127], v[126:127], v[50:51], v[132:133]
	v_lshlrev_b32_e32 v132, 16, v140
	v_and_b32_e32 v133, 0xffff0000, v140
	v_lshlrev_b32_e32 v138, 16, v141
	v_and_b32_e32 v139, 0xffff0000, v141
	v_pk_fma_f32 v[124:125], v[124:125], v[56:57], v[138:139]
	v_pk_fma_f32 v[122:123], v[122:123], v[54:55], v[132:133]
	v_lshl_add_u64 v[132:133], v[134:135], 2, s[16:17]
	s_cbranch_vccnz .LBB0_778
	global_store_dwordx4 v[132:133], v[126:129], off nt
	global_store_dwordx4 v[132:133], v[122:125], off offset:16 nt
	v_mov_b32_e32 v138, 0
	s_cbranch_execnz .LBB0_706

.LBB0_706:
	v_lshlrev_b64 v[122:123], 1, v[134:135]
	v_or_b32_e32 v122, 0x100, v122
	v_lshl_add_u64 v[122:123], s[28:29], 0, v[122:123]
	s_and_b64 vcc, exec, s[38:39]
	s_waitcnt vmcnt(7)
	v_mov_b32_e32 v124, v220
	v_mov_b32_e32 v125, v221
	v_mov_b32_e32 v126, v222
	v_mov_b32_e32 v127, v223
	v_lshlrev_b32_e32 v128, 16, v124
	v_and_b32_e32 v129, 0xffff0000, v124
	v_lshlrev_b32_e32 v124, 16, v125
	v_and_b32_e32 v125, 0xffff0000, v125
	v_pk_fma_f32 v[120:121], v[120:121], v[40:41], v[124:125]
	v_lshlrev_b32_e32 v124, 16, v126
	v_and_b32_e32 v125, 0xffff0000, v126
	v_lshlrev_b32_e32 v126, 16, v127
	v_and_b32_e32 v127, 0xffff0000, v127
	v_pk_fma_f32 v[118:119], v[118:119], v[38:39], v[128:129]
	v_pk_fma_f32 v[116:117], v[116:117], v[48:49], v[126:127]
	v_pk_fma_f32 v[114:115], v[114:115], v[46:47], v[124:125]
	s_cbranch_vccnz .LBB0_779
	global_store_dwordx4 v[132:133], v[118:121], off offset:512 nt
	global_store_dwordx4 v[132:133], v[114:117], off offset:528 nt
	s_cbranch_execnz .LBB0_709

.LBB0_713:
	v_or_b32_e32 v114, 32, v166
	s_waitcnt lgkmcnt(0)
	v_ashrrev_i32_e32 v115, 31, v114
	v_lshlrev_b64 v[116:117], 10, v[114:115]
	v_lshl_add_u64 v[118:119], v[116:117], 0, v[164:165]
	v_lshl_add_u64 v[120:121], v[118:119], 1, s[28:29]
	s_and_b64 vcc, exec, s[38:39]
	s_waitcnt vmcnt(7)
	v_mov_b32_e32 v122, v224
	v_mov_b32_e32 v123, v225
	v_mov_b32_e32 v124, v226
	v_mov_b32_e32 v125, v227
	v_lshlrev_b32_e32 v116, 16, v122
	v_and_b32_e32 v117, 0xffff0000, v122
	v_lshlrev_b32_e32 v122, 16, v123
	v_and_b32_e32 v123, 0xffff0000, v123
	v_pk_fma_f32 v[112:113], v[112:113], v[52:53], v[122:123]
	v_pk_fma_f32 v[110:111], v[110:111], v[50:51], v[116:117]
	v_lshlrev_b32_e32 v116, 16, v124
	v_and_b32_e32 v117, 0xffff0000, v124
	v_lshlrev_b32_e32 v122, 16, v125
	v_and_b32_e32 v123, 0xffff0000, v125
	v_pk_fma_f32 v[108:109], v[108:109], v[56:57], v[122:123]
	v_pk_fma_f32 v[106:107], v[106:107], v[54:55], v[116:117]
	v_lshl_add_u64 v[116:117], v[118:119], 2, s[16:17]
	s_cbranch_vccnz .LBB0_780
	global_store_dwordx4 v[116:117], v[110:113], off nt
	global_store_dwordx4 v[116:117], v[106:109], off offset:16 nt
	v_mov_b32_e32 v122, 0
	s_cbranch_execnz .LBB0_716

.LBB0_716:
	v_lshlrev_b64 v[106:107], 1, v[118:119]
	v_or_b32_e32 v106, 0x100, v106
	v_lshl_add_u64 v[106:107], s[28:29], 0, v[106:107]
	s_and_b64 vcc, exec, s[38:39]
	s_waitcnt vmcnt(7)
	v_mov_b32_e32 v108, v228
	v_mov_b32_e32 v109, v229
	v_mov_b32_e32 v110, v230
	v_mov_b32_e32 v111, v231
	v_lshlrev_b32_e32 v112, 16, v108
	v_and_b32_e32 v113, 0xffff0000, v108
	v_lshlrev_b32_e32 v108, 16, v109
	v_and_b32_e32 v109, 0xffff0000, v109
	v_pk_fma_f32 v[104:105], v[104:105], v[40:41], v[108:109]
	v_lshlrev_b32_e32 v108, 16, v110
	v_and_b32_e32 v109, 0xffff0000, v110
	v_lshlrev_b32_e32 v110, 16, v111
	v_and_b32_e32 v111, 0xffff0000, v111
	v_pk_fma_f32 v[102:103], v[102:103], v[38:39], v[112:113]
	v_pk_fma_f32 v[100:101], v[100:101], v[48:49], v[110:111]
	v_pk_fma_f32 v[98:99], v[98:99], v[46:47], v[108:109]
	s_cbranch_vccnz .LBB0_781
	global_store_dwordx4 v[116:117], v[102:105], off offset:512 nt
	global_store_dwordx4 v[116:117], v[98:101], off offset:528 nt
	s_cbranch_execnz .LBB0_719

.LBB0_723:
	v_or_b32_e32 v98, 48, v166
	s_waitcnt lgkmcnt(0)
	v_ashrrev_i32_e32 v99, 31, v98
	v_lshlrev_b64 v[100:101], 10, v[98:99]
	v_lshl_add_u64 v[102:103], v[100:101], 0, v[164:165]
	v_lshl_add_u64 v[104:105], v[102:103], 1, s[28:29]
	s_and_b64 vcc, exec, s[38:39]
	s_waitcnt vmcnt(7)
	v_mov_b32_e32 v106, v232
	v_mov_b32_e32 v107, v233
	v_mov_b32_e32 v108, v234
	v_mov_b32_e32 v109, v235
	v_lshlrev_b32_e32 v100, 16, v106
	v_and_b32_e32 v101, 0xffff0000, v106
	v_lshlrev_b32_e32 v106, 16, v107
	v_and_b32_e32 v107, 0xffff0000, v107
	v_pk_fma_f32 v[96:97], v[96:97], v[52:53], v[106:107]
	v_pk_fma_f32 v[94:95], v[94:95], v[50:51], v[100:101]
	v_lshlrev_b32_e32 v100, 16, v108
	v_and_b32_e32 v101, 0xffff0000, v108
	v_lshlrev_b32_e32 v106, 16, v109
	v_and_b32_e32 v107, 0xffff0000, v109
	v_pk_fma_f32 v[92:93], v[92:93], v[56:57], v[106:107]
	v_pk_fma_f32 v[90:91], v[90:91], v[54:55], v[100:101]
	v_lshl_add_u64 v[100:101], v[102:103], 2, s[16:17]
	s_cbranch_vccnz .LBB0_782
	global_store_dwordx4 v[100:101], v[94:97], off nt
	global_store_dwordx4 v[100:101], v[90:93], off offset:16 nt
	v_mov_b32_e32 v106, 0
	s_cbranch_execnz .LBB0_726

.LBB0_726:
	v_lshlrev_b64 v[90:91], 1, v[102:103]
	v_or_b32_e32 v90, 0x100, v90
	v_lshl_add_u64 v[90:91], s[28:29], 0, v[90:91]
	s_and_b64 vcc, exec, s[38:39]
	s_waitcnt vmcnt(7)
	v_mov_b32_e32 v92, v236
	v_mov_b32_e32 v93, v237
	v_mov_b32_e32 v94, v238
	v_mov_b32_e32 v95, v239
	s_mov_b64 s[98:99], 0x40000
	v_lshl_add_u64 v[182:183], v[198:199], 0, s[98:99]
	s_mov_b64 s[42:43], 0x8000
	global_load_dwordx4 v[184:187], v[182:183], off
	global_load_dwordx4 v[212:215], v[182:183], off offset:256
	v_lshl_add_u64 v[182:183], v[182:183], 0, s[42:43]
	global_load_dwordx4 v[216:219], v[182:183], off
	global_load_dwordx4 v[220:223], v[182:183], off offset:256
	v_lshl_add_u64 v[182:183], v[182:183], 0, s[42:43]
	global_load_dwordx4 v[224:227], v[182:183], off
	global_load_dwordx4 v[228:231], v[182:183], off offset:256
	v_lshl_add_u64 v[182:183], v[182:183], 0, s[42:43]
	global_load_dwordx4 v[232:235], v[182:183], off
	global_load_dwordx4 v[236:239], v[182:183], off offset:256
	v_lshlrev_b32_e32 v96, 16, v92
	v_and_b32_e32 v97, 0xffff0000, v92
	v_lshlrev_b32_e32 v92, 16, v93
	v_and_b32_e32 v93, 0xffff0000, v93
	v_pk_fma_f32 v[88:89], v[88:89], v[40:41], v[92:93]
	v_lshlrev_b32_e32 v92, 16, v94
	v_and_b32_e32 v93, 0xffff0000, v94
	v_lshlrev_b32_e32 v94, 16, v95
	v_and_b32_e32 v95, 0xffff0000, v95
	v_pk_fma_f32 v[86:87], v[86:87], v[38:39], v[96:97]
	v_pk_fma_f32 v[84:85], v[84:85], v[48:49], v[94:95]
	v_pk_fma_f32 v[82:83], v[82:83], v[46:47], v[92:93]
	s_cbranch_vccnz .LBB0_783
	global_store_dwordx4 v[100:101], v[86:89], off offset:512 nt
	global_store_dwordx4 v[100:101], v[82:85], off offset:528 nt
	s_cbranch_execnz .LBB0_729

.LBB0_733:
	v_add_u32_e32 v82, 0x80, v166
	s_waitcnt lgkmcnt(0)
	v_ashrrev_i32_e32 v83, 31, v82
	v_lshlrev_b64 v[84:85], 10, v[82:83]
	v_lshl_add_u64 v[86:87], v[84:85], 0, v[164:165]
	v_lshl_add_u64 v[88:89], v[86:87], 1, s[28:29]
	s_and_b64 vcc, exec, s[38:39]
	s_waitcnt vmcnt(7)
	v_mov_b32_e32 v90, v184
	v_mov_b32_e32 v91, v185
	v_mov_b32_e32 v92, v186
	v_mov_b32_e32 v93, v187
	v_lshlrev_b32_e32 v84, 16, v90
	v_and_b32_e32 v85, 0xffff0000, v90
	v_lshlrev_b32_e32 v90, 16, v91
	v_and_b32_e32 v91, 0xffff0000, v91
	v_pk_fma_f32 v[80:81], v[80:81], v[52:53], v[90:91]
	v_pk_fma_f32 v[78:79], v[78:79], v[50:51], v[84:85]
	v_lshlrev_b32_e32 v84, 16, v92
	v_and_b32_e32 v85, 0xffff0000, v92
	v_lshlrev_b32_e32 v90, 16, v93
	v_and_b32_e32 v91, 0xffff0000, v93
	v_pk_fma_f32 v[76:77], v[76:77], v[56:57], v[90:91]
	v_pk_fma_f32 v[74:75], v[74:75], v[54:55], v[84:85]
	v_lshl_add_u64 v[84:85], v[86:87], 2, s[16:17]
	s_cbranch_vccnz .LBB0_784
	global_store_dwordx4 v[84:85], v[78:81], off nt
	global_store_dwordx4 v[84:85], v[74:77], off offset:16 nt
	v_mov_b32_e32 v90, 0
	s_cbranch_execnz .LBB0_736

.LBB0_736:
	v_lshlrev_b64 v[74:75], 1, v[86:87]
	v_or_b32_e32 v74, 0x100, v74
	v_lshl_add_u64 v[74:75], s[28:29], 0, v[74:75]
	s_and_b64 vcc, exec, s[38:39]
	s_waitcnt vmcnt(7)
	v_mov_b32_e32 v76, v212
	v_mov_b32_e32 v77, v213
	v_mov_b32_e32 v78, v214
	v_mov_b32_e32 v79, v215
	v_lshlrev_b32_e32 v80, 16, v76
	v_and_b32_e32 v81, 0xffff0000, v76
	v_lshlrev_b32_e32 v76, 16, v77
	v_and_b32_e32 v77, 0xffff0000, v77
	v_pk_fma_f32 v[72:73], v[72:73], v[40:41], v[76:77]
	v_lshlrev_b32_e32 v76, 16, v78
	v_and_b32_e32 v77, 0xffff0000, v78
	v_lshlrev_b32_e32 v78, 16, v79
	v_and_b32_e32 v79, 0xffff0000, v79
	v_pk_fma_f32 v[70:71], v[70:71], v[38:39], v[80:81]
	v_pk_fma_f32 v[68:69], v[68:69], v[48:49], v[78:79]
	v_pk_fma_f32 v[66:67], v[66:67], v[46:47], v[76:77]
	s_cbranch_vccnz .LBB0_785
	global_store_dwordx4 v[84:85], v[70:73], off offset:512 nt
	global_store_dwordx4 v[84:85], v[66:69], off offset:528 nt
	s_cbranch_execnz .LBB0_739

.LBB0_743:
	v_add_u32_e32 v66, 0x90, v166
	s_waitcnt lgkmcnt(0)
	v_ashrrev_i32_e32 v67, 31, v66
	v_lshlrev_b64 v[68:69], 10, v[66:67]
	v_lshl_add_u64 v[70:71], v[68:69], 0, v[164:165]
	v_lshl_add_u64 v[72:73], v[70:71], 1, s[28:29]
	s_and_b64 vcc, exec, s[38:39]
	s_waitcnt vmcnt(7)
	v_mov_b32_e32 v74, v216
	v_mov_b32_e32 v75, v217
	v_mov_b32_e32 v76, v218
	v_mov_b32_e32 v77, v219
	v_lshlrev_b32_e32 v68, 16, v74
	v_and_b32_e32 v69, 0xffff0000, v74
	v_lshlrev_b32_e32 v74, 16, v75
	v_and_b32_e32 v75, 0xffff0000, v75
	v_pk_fma_f32 v[64:65], v[64:65], v[52:53], v[74:75]
	v_pk_fma_f32 v[62:63], v[62:63], v[50:51], v[68:69]
	v_lshlrev_b32_e32 v68, 16, v76
	v_and_b32_e32 v69, 0xffff0000, v76
	v_lshlrev_b32_e32 v74, 16, v77
	v_and_b32_e32 v75, 0xffff0000, v77
	v_pk_fma_f32 v[60:61], v[60:61], v[56:57], v[74:75]
	v_pk_fma_f32 v[58:59], v[58:59], v[54:55], v[68:69]
	v_lshl_add_u64 v[68:69], v[70:71], 2, s[16:17]
	s_cbranch_vccnz .LBB0_786
	global_store_dwordx4 v[68:69], v[62:65], off nt
	global_store_dwordx4 v[68:69], v[58:61], off offset:16 nt
	v_mov_b32_e32 v74, 0
	s_cbranch_execnz .LBB0_746

.LBB0_746:
	v_lshlrev_b64 v[58:59], 1, v[70:71]
	v_or_b32_e32 v58, 0x100, v58
	v_lshl_add_u64 v[58:59], s[28:29], 0, v[58:59]
	s_and_b64 vcc, exec, s[38:39]
	s_waitcnt vmcnt(7)
	v_mov_b32_e32 v60, v220
	v_mov_b32_e32 v61, v221
	v_mov_b32_e32 v62, v222
	v_mov_b32_e32 v63, v223
	v_lshlrev_b32_e32 v64, 16, v60
	v_and_b32_e32 v65, 0xffff0000, v60
	v_lshlrev_b32_e32 v60, 16, v61
	v_and_b32_e32 v61, 0xffff0000, v61
	v_pk_fma_f32 v[44:45], v[44:45], v[40:41], v[60:61]
	v_lshlrev_b32_e32 v60, 16, v62
	v_and_b32_e32 v61, 0xffff0000, v62
	v_lshlrev_b32_e32 v62, 16, v63
	v_and_b32_e32 v63, 0xffff0000, v63
	v_pk_fma_f32 v[42:43], v[42:43], v[38:39], v[64:65]
	v_pk_fma_f32 v[36:37], v[36:37], v[48:49], v[62:63]
	v_pk_fma_f32 v[34:35], v[34:35], v[46:47], v[60:61]
	s_cbranch_vccnz .LBB0_787
	global_store_dwordx4 v[68:69], v[42:45], off offset:512 nt
	global_store_dwordx4 v[68:69], v[34:37], off offset:528 nt
	s_cbranch_execnz .LBB0_749

.LBB0_753:
	v_add_u32_e32 v34, 0xa0, v166
	s_waitcnt lgkmcnt(0)
	v_ashrrev_i32_e32 v35, 31, v34
	v_lshlrev_b64 v[36:37], 10, v[34:35]
	v_lshl_add_u64 v[42:43], v[36:37], 0, v[164:165]
	v_lshl_add_u64 v[44:45], v[42:43], 1, s[28:29]
	s_and_b64 vcc, exec, s[38:39]
	s_waitcnt vmcnt(7)
	v_mov_b32_e32 v58, v224
	v_mov_b32_e32 v59, v225
	v_mov_b32_e32 v60, v226
	v_mov_b32_e32 v61, v227
	v_lshlrev_b32_e32 v36, 16, v58
	v_and_b32_e32 v37, 0xffff0000, v58
	v_lshlrev_b32_e32 v58, 16, v59
	v_and_b32_e32 v59, 0xffff0000, v59
	v_pk_fma_f32 v[32:33], v[32:33], v[52:53], v[58:59]
	v_pk_fma_f32 v[30:31], v[30:31], v[50:51], v[36:37]
	v_lshlrev_b32_e32 v36, 16, v60
	v_and_b32_e32 v37, 0xffff0000, v60
	v_lshlrev_b32_e32 v58, 16, v61
	v_and_b32_e32 v59, 0xffff0000, v61
	v_pk_fma_f32 v[28:29], v[28:29], v[56:57], v[58:59]
	v_pk_fma_f32 v[26:27], v[26:27], v[54:55], v[36:37]
	v_lshl_add_u64 v[36:37], v[42:43], 2, s[16:17]
	s_cbranch_vccnz .LBB0_788
	global_store_dwordx4 v[36:37], v[30:33], off nt
	global_store_dwordx4 v[36:37], v[26:29], off offset:16 nt
	v_mov_b32_e32 v58, 0
	s_cbranch_execnz .LBB0_756

.LBB0_756:
	v_lshlrev_b64 v[26:27], 1, v[42:43]
	v_or_b32_e32 v26, 0x100, v26
	v_lshl_add_u64 v[26:27], s[28:29], 0, v[26:27]
	s_and_b64 vcc, exec, s[38:39]
	s_waitcnt vmcnt(7)
	v_mov_b32_e32 v28, v228
	v_mov_b32_e32 v29, v229
	v_mov_b32_e32 v30, v230
	v_mov_b32_e32 v31, v231
	v_lshlrev_b32_e32 v32, 16, v28
	v_and_b32_e32 v33, 0xffff0000, v28
	v_lshlrev_b32_e32 v28, 16, v29
	v_and_b32_e32 v29, 0xffff0000, v29
	v_pk_fma_f32 v[24:25], v[24:25], v[40:41], v[28:29]
	v_lshlrev_b32_e32 v28, 16, v30
	v_and_b32_e32 v29, 0xffff0000, v30
	v_lshlrev_b32_e32 v30, 16, v31
	v_and_b32_e32 v31, 0xffff0000, v31
	v_pk_fma_f32 v[22:23], v[22:23], v[38:39], v[32:33]
	v_pk_fma_f32 v[20:21], v[20:21], v[48:49], v[30:31]
	v_pk_fma_f32 v[18:19], v[18:19], v[46:47], v[28:29]
	s_cbranch_vccnz .LBB0_789
	global_store_dwordx4 v[36:37], v[22:25], off offset:512 nt
	global_store_dwordx4 v[36:37], v[18:21], off offset:528 nt
	s_cbranch_execnz .LBB0_759

.LBB0_763:
	v_add_u32_e32 v18, 0xb0, v166
	s_waitcnt lgkmcnt(0)
	v_ashrrev_i32_e32 v19, 31, v18
	v_lshlrev_b64 v[20:21], 10, v[18:19]
	v_lshl_add_u64 v[22:23], v[20:21], 0, v[164:165]
	v_lshl_add_u64 v[24:25], v[22:23], 1, s[28:29]
	s_and_b64 vcc, exec, s[38:39]
	s_waitcnt vmcnt(7)
	v_mov_b32_e32 v26, v232
	v_mov_b32_e32 v27, v233
	v_mov_b32_e32 v28, v234
	v_mov_b32_e32 v29, v235
	v_lshlrev_b32_e32 v20, 16, v26
	v_and_b32_e32 v21, 0xffff0000, v26
	v_lshlrev_b32_e32 v26, 16, v27
	v_and_b32_e32 v27, 0xffff0000, v27
	v_pk_fma_f32 v[16:17], v[16:17], v[52:53], v[26:27]
	v_pk_fma_f32 v[14:15], v[14:15], v[50:51], v[20:21]
	v_lshlrev_b32_e32 v20, 16, v28
	v_and_b32_e32 v21, 0xffff0000, v28
	v_lshlrev_b32_e32 v26, 16, v29
	v_and_b32_e32 v27, 0xffff0000, v29
	v_pk_fma_f32 v[12:13], v[12:13], v[56:57], v[26:27]
	v_pk_fma_f32 v[10:11], v[10:11], v[54:55], v[20:21]
	v_lshl_add_u64 v[20:21], v[22:23], 2, s[16:17]
	s_cbranch_vccnz .LBB0_790
	global_store_dwordx4 v[20:21], v[14:17], off nt
	global_store_dwordx4 v[20:21], v[10:13], off offset:16 nt
	v_mov_b32_e32 v26, 0
	s_cbranch_execnz .LBB0_766

.LBB0_766:
	v_lshlrev_b64 v[10:11], 1, v[22:23]
	v_or_b32_e32 v10, 0x100, v10
	v_lshl_add_u64 v[10:11], s[28:29], 0, v[10:11]
	s_and_b64 vcc, exec, s[38:39]
	s_waitcnt vmcnt(7)
	v_mov_b32_e32 v12, v236
	v_mov_b32_e32 v13, v237
	v_mov_b32_e32 v14, v238
	v_mov_b32_e32 v15, v239
	v_lshlrev_b32_e32 v16, 16, v12
	v_and_b32_e32 v17, 0xffff0000, v12
	v_lshlrev_b32_e32 v12, 16, v13
	v_and_b32_e32 v13, 0xffff0000, v13
	v_pk_fma_f32 v[8:9], v[8:9], v[40:41], v[12:13]
	v_lshlrev_b32_e32 v12, 16, v14
	v_and_b32_e32 v13, 0xffff0000, v14
	v_lshlrev_b32_e32 v14, 16, v15
	v_and_b32_e32 v15, 0xffff0000, v15
	v_pk_fma_f32 v[6:7], v[6:7], v[38:39], v[16:17]
	v_pk_fma_f32 v[4:5], v[4:5], v[48:49], v[14:15]
	v_pk_fma_f32 v[2:3], v[2:3], v[46:47], v[12:13]
	s_cbranch_vccnz .LBB0_791
	global_store_dwordx4 v[20:21], v[6:9], off offset:512 nt
	global_store_dwordx4 v[20:21], v[2:5], off offset:528 nt
	s_cbranch_execnz .LBB0_769
